# P7 second-row loads hoisted next to the first row's (two rows in flight) + the v111 policies
# baseline (speedup 1.0000x reference)
.LBB0_807:
	s_ashr_i32 s7, s6, 31
	s_lshl_b64 s[0:1], s[6:7], 6
	s_waitcnt lgkmcnt(0)
	v_lshl_add_u64 v[16:17], v[24:25], 0, s[0:1]
	global_load_dwordx4 v[30:33], v[16:17], off
	s_add_i32 s12, s3, s6
	s_cmp_lt_i32 s12, 0x8000
	s_cselect_b32 s0, s12, s6
	s_ashr_i32 s1, s0, 31
	s_lshl_b64 s[20:21], s[0:1], 6
	s_lshl_b64 s[14:15], s[0:1], 11
	s_lshl_b64 s[0:1], s[0:1], 2
	s_add_u32 s16, s30, s0
	s_addc_u32 s17, s31, s1
	s_lshl_b64 s[0:1], s[6:7], 11
	v_lshl_add_u64 v[28:29], v[22:23], 0, s[0:1]
	global_load_dwordx2 v[34:35], v[28:29], off offset:1536
	v_lshl_add_u64 v[16:17], v[26:27], 0, s[0:1]
	s_lshl_b64 s[0:1], s[6:7], 2
	s_add_u32 s0, s30, s0
	s_addc_u32 s1, s31, s1
	global_load_dwordx2 v[36:37], v[16:17], off offset:512
	global_load_dwordx2 v[38:39], v[28:29], off offset:512
	global_load_dwordx2 v[40:41], v[16:17], off offset:1024
	global_load_dwordx2 v[42:43], v[28:29], off offset:1024
	global_load_dwordx2 v[44:45], v[16:17], off offset:1536
	global_load_dwordx2 v[46:47], v[28:29], off
	global_load_dwordx2 v[56:57], v[16:17], off
	global_load_dword v58, v21, s[0:1]
	v_lshl_add_u64 v[16:17], v[24:25], 0, s[20:21]
	global_load_dwordx4 v[16:19], v[16:17], off
	v_lshl_add_u64 v[100:101], v[22:23], 0, s[14:15]
	v_lshl_add_u64 v[102:103], v[26:27], 0, s[14:15]
	global_load_dword v90, v21, s[16:17]
	global_load_dwordx2 v[92:93], v[100:101], off
	global_load_dwordx2 v[94:95], v[100:101], off offset:512
	global_load_dwordx2 v[96:97], v[100:101], off offset:1024
	global_load_dwordx2 v[98:99], v[100:101], off offset:1536
	global_load_dwordx2 v[104:105], v[102:103], off
	global_load_dwordx2 v[106:107], v[102:103], off offset:512
	global_load_dwordx2 v[108:109], v[102:103], off offset:1024
	global_load_dwordx2 v[110:111], v[102:103], off offset:1536
	s_cmpk_gt_i32 s12, 0x7fff
	s_waitcnt vmcnt(19)
	v_mov_b32_e32 v60, v31
	v_mov_b32_e32 v61, v32
	v_mov_b32_e32 v31, v33
	v_pk_add_f32 v[30:31], v[60:61], v[30:31]
	s_waitcnt vmcnt(17)
	v_and_b32_e32 v61, 0xffff0000, v36
	v_add_f32_e32 v30, v30, v31
	ds_bpermute_b32 v32, v20, v30
	v_and_b32_e32 v55, 0xffff0000, v35
	v_lshlrev_b32_e32 v59, 16, v35
	s_waitcnt vmcnt(13)
	v_lshlrev_b32_e32 v70, 16, v44
	v_and_b32_e32 v72, 0xffff0000, v44
	s_waitcnt lgkmcnt(0)
	v_add_f32_e32 v30, v30, v32
	ds_bpermute_b32 v32, v48, v30
	v_lshlrev_b32_e32 v74, 16, v45
	v_and_b32_e32 v76, 0xffff0000, v45
	s_waitcnt vmcnt(11)
	v_lshlrev_b32_e32 v44, 16, v57
	v_and_b32_e32 v45, 0xffff0000, v57
	s_waitcnt lgkmcnt(0)
	v_add_f32_e32 v30, v30, v32
	v_fmamk_f32 v30, v30, 0x3a800000, v53
	v_mul_f32_e32 v32, 0x4f800000, v30
	v_cmp_gt_f32_e32 vcc, s19, v30
	s_waitcnt vmcnt(10)
	v_mul_f32_e32 v57, v58, v55
	v_and_b32_e32 v31, 0xffff0000, v34
	v_cndmask_b32_e32 v30, v30, v32, vcc
	v_sqrt_f32_e32 v32, v30
	v_lshlrev_b32_e32 v33, 16, v34
	v_lshlrev_b32_e32 v35, 16, v36
	v_lshlrev_b32_e32 v34, 16, v38
	v_add_u32_e32 v55, -1, v32
	v_and_b32_e32 v60, 0xffff0000, v38
	v_lshlrev_b32_e32 v62, 16, v39
	v_and_b32_e32 v36, 0xffff0000, v39
	v_lshlrev_b32_e32 v39, 16, v40
	v_lshlrev_b32_e32 v38, 16, v42
	v_and_b32_e32 v65, 0xffff0000, v40
	v_and_b32_e32 v64, 0xffff0000, v42
	v_lshlrev_b32_e32 v66, 16, v43
	v_and_b32_e32 v40, 0xffff0000, v43
	v_lshlrev_b32_e32 v42, 16, v47
	v_and_b32_e32 v43, 0xffff0000, v47
	v_lshlrev_b32_e32 v68, 16, v46
	v_and_b32_e32 v69, 0xffff0000, v46
	v_lshlrev_b32_e32 v46, 16, v56
	v_and_b32_e32 v47, 0xffff0000, v56
	v_mul_f32_e32 v71, v58, v59
	v_add_u32_e32 v56, 1, v32
	v_fma_f32 v59, -v55, v32, v30
	v_fma_f32 v73, -v56, v32, v30
	v_cmp_ge_f32_e64 s[0:1], 0, v59
	v_lshlrev_b32_e32 v63, 16, v37
	v_and_b32_e32 v37, 0xffff0000, v37
	v_cndmask_b32_e64 v32, v32, v55, s[0:1]
	v_cmp_lt_f32_e64 s[0:1], 0, v73
	v_lshlrev_b32_e32 v67, 16, v41
	v_and_b32_e32 v41, 0xffff0000, v41
	v_cndmask_b32_e64 v32, v32, v56, s[0:1]
	v_mul_f32_e32 v55, 0x37800000, v32
	v_cndmask_b32_e32 v32, v32, v55, vcc
	v_cmp_class_f32_e32 vcc, v30, v54
	v_mov_b32_e32 v73, v58
	s_waitcnt vmcnt(9)
	v_add_f32_e32 v16, v16, v17
	v_cndmask_b32_e32 v30, v32, v30, vcc
	v_div_scale_f32 v32, s[0:1], v30, v30, 1.0
	v_rcp_f32_e32 v55, v32
	v_div_scale_f32 v56, vcc, 1.0, v30, 1.0
	v_add_f32_e32 v18, v18, v19
	v_fma_f32 v59, -v32, v55, 1.0
	v_fmac_f32_e32 v55, v59, v55
	v_mul_f32_e32 v59, v56, v55
	v_fma_f32 v75, -v32, v59, v56
	v_fmac_f32_e32 v59, v75, v55
	v_fma_f32 v32, -v32, v59, v56
	v_div_fmas_f32 v32, v32, v55, v59
	v_div_fixup_f32 v59, v32, v30, 1.0
	v_mov_b32_e32 v30, v59
	v_mul_f32_e32 v32, v59, v74
	v_pk_mul_f32 v[44:45], v[30:31], v[44:45] op_sel_hi:[0,1]
	v_pk_mul_f32 v[34:35], v[58:59], v[34:35]
	v_pk_mul_f32 v[60:61], v[58:59], v[60:61]
	v_pk_mul_f32 v[62:63], v[58:59], v[62:63]
	v_pk_mul_f32 v[36:37], v[58:59], v[36:37]
	v_pk_mul_f32 v[38:39], v[58:59], v[38:39]
	v_pk_mul_f32 v[64:65], v[58:59], v[64:65]
	v_pk_mul_f32 v[66:67], v[58:59], v[66:67]
	v_pk_mul_f32 v[40:41], v[58:59], v[40:41]
	v_mul_f32_e32 v75, v59, v70
	v_mul_f32_e32 v77, v59, v72
	v_mul_f32_e32 v55, v59, v76
	v_mul_f32_e32 v59, v2, v32
	v_pk_mul_f32 v[46:47], v[30:31], v[46:47] op_sel_hi:[0,1]
	v_pk_mul_f32 v[44:45], v[14:15], v[44:45]
	v_pk_mul_f32 v[46:47], v[12:13], v[46:47]
	v_pk_fma_f32 v[80:81], v[58:59], v[42:43], v[44:45] op_sel_hi:[0,1,1]
	v_pk_fma_f32 v[68:69], v[58:59], v[68:69], v[46:47] op_sel_hi:[0,1,1]
	v_pk_mov_b32 v[42:43], v[80:81], v[0:1] op_sel:[1,0]
	v_mov_b32_e32 v74, v81
	v_pk_mul_f32 v[42:43], v[42:43], v[74:75]
	v_pk_mov_b32 v[82:83], v[68:69], v[0:1] op_sel:[1,0]
	v_mov_b32_e32 v74, v69
	v_mov_b32_e32 v72, v80
	v_mov_b32_e32 v32, v80
	v_mov_b32_e32 v44, v68
	v_mov_b32_e32 v45, v58
	v_mov_b32_e32 v46, v68
	v_mov_b32_e32 v47, v33
	v_pk_mul_f32 v[74:75], v[82:83], v[74:75]
	v_pk_fma_f32 v[32:33], v[72:73], v[32:33], v[42:43]
	v_pk_fma_f32 v[72:73], v[44:45], v[46:47], v[74:75]
	v_mul_f32_e32 v79, v3, v55
	v_pk_add_f32 v[42:43], v[72:73], v[32:33]
	v_pk_mul_f32 v[32:33], v[72:73], v[32:33]
	v_add_f32_e32 v16, v16, v18
	v_mov_b32_e32 v43, v33
	v_mov_b32_e32 v32, v63
	v_mov_b32_e32 v33, v37
	v_mov_b32_e32 v63, v36
	v_mov_b32_e32 v36, v35
	v_mov_b32_e32 v37, v61
	v_mov_b32_e32 v35, v60
	v_pk_fma_f32 v[60:61], v[8:9], v[36:37], v[34:35]
	v_pk_fma_f32 v[62:63], v[10:11], v[32:33], v[62:63]
	v_mov_b32_e32 v36, v61
	v_mov_b32_e32 v37, v1
	v_mov_b32_e32 v76, v61
	v_mov_b32_e32 v32, v63
	v_mov_b32_e32 v33, v1
	v_mov_b32_e32 v34, v60
	v_mov_b32_e32 v35, v58
	v_mov_b32_e32 v30, v60
	v_pk_mul_f32 v[36:37], v[36:37], v[76:77]
	v_mov_b32_e32 v76, v63
	v_pk_fma_f32 v[74:75], v[34:35], v[30:31], v[36:37]
	v_mov_b32_e32 v34, v62
	v_mov_b32_e32 v30, v62
	v_pk_mul_f32 v[32:33], v[32:33], v[76:77]
	ds_bpermute_b32 v18, v20, v16
	v_pk_fma_f32 v[30:31], v[34:35], v[30:31], v[32:33]
	s_waitcnt lgkmcnt(0)
	v_add_f32_e32 v16, v16, v18
	v_pk_add_f32 v[32:33], v[74:75], v[30:31]
	v_pk_mul_f32 v[30:31], v[74:75], v[30:31]
	v_mov_b32_e32 v74, v73
	v_mov_b32_e32 v33, v31
	v_pk_add_f32 v[30:31], v[42:43], v[32:33]
	v_mov_b32_e32 v32, v67
	v_mov_b32_e32 v33, v41
	v_mov_b32_e32 v67, v40
	v_pk_fma_f32 v[66:67], v[6:7], v[32:33], v[66:67]
	s_nop 0
	v_mov_b32_e32 v78, v66
	v_mov_b32_e32 v56, v66
	v_pk_add_f32 v[56:57], v[78:79], v[56:57]
	v_mul_f32_e32 v32, v67, v67
	v_pk_fma_f32 v[32:33], v[66:67], v[66:67], v[32:33] op_sel_hi:[1,1,0]
	v_pk_mul_f32 v[34:35], v[56:57], v[56:57]
	s_nop 0
	v_mov_b32_e32 v33, v35
	v_mov_b32_e32 v34, v39
	v_mov_b32_e32 v35, v65
	v_mov_b32_e32 v39, v64
	v_pk_fma_f32 v[64:65], v[4:5], v[34:35], v[38:39]
	s_nop 0
	v_mov_b32_e32 v58, v64
	v_mov_b32_e32 v70, v64
	v_pk_add_f32 v[58:59], v[58:59], v[70:71]
	v_mul_f32_e32 v34, v65, v65
	v_pk_fma_f32 v[34:35], v[64:65], v[64:65], v[34:35] op_sel_hi:[1,1,0]
	v_pk_mul_f32 v[36:37], v[58:59], v[58:59]
	v_lshl_add_u64 v[70:71], v[26:27], 0, s[14:15]
	v_mov_b32_e32 v35, v37
	v_pk_add_f32 v[32:33], v[34:35], v[32:33]
	v_lshl_add_u64 v[34:35], v[22:23], 0, s[14:15]
	v_pk_add_f32 v[30:31], v[30:31], v[32:33]
	s_nop 0
	v_add_f32_e32 v31, v30, v31
	ds_bpermute_b32 v32, v20, v31
	s_waitcnt vmcnt(0)
	v_mov_b32_e32 v30, v90
	s_waitcnt lgkmcnt(0)
	v_add_f32_e32 v31, v31, v32
	ds_bpermute_b32 v36, v48, v31
	v_mov_b64_e32 v[32:33], v[92:93]
	v_mov_b64_e32 v[42:43], v[94:95]
	v_mov_b64_e32 v[38:39], v[96:97]
	v_mov_b64_e32 v[46:47], v[98:99]
	s_waitcnt lgkmcnt(0)
	v_add_f32_e32 v31, v31, v36
	v_mov_b64_e32 v[34:35], v[104:105]
	v_mov_b64_e32 v[44:45], v[106:107]
	v_mov_b64_e32 v[40:41], v[108:109]
	v_mov_b64_e32 v[36:37], v[110:111]
	ds_bpermute_b32 v55, v49, v31
	s_waitcnt lgkmcnt(0)
	v_add_f32_e32 v31, v31, v55
	ds_bpermute_b32 v55, v50, v31
	s_waitcnt lgkmcnt(0)
	v_add_f32_e32 v31, v31, v55
	ds_bpermute_b32 v55, v51, v31
	s_waitcnt lgkmcnt(0)
	v_add_f32_e32 v31, v31, v55
	ds_bpermute_b32 v55, v52, v31
	s_waitcnt lgkmcnt(0)
	v_add_f32_e32 v17, v31, v55
	v_fmamk_f32 v17, v17, 0x3a800000, v53
	v_mul_f32_e32 v31, 0x4f800000, v17
	v_cmp_gt_f32_e32 vcc, s19, v17
	s_nop 1
	v_cndmask_b32_e32 v17, v17, v31, vcc
	v_sqrt_f32_e32 v31, v17
	s_nop 0
	v_add_u32_e32 v19, -1, v31
	v_fma_f32 v55, -v19, v31, v17
	v_cmp_ge_f32_e64 s[0:1], 0, v55
	v_add_u32_e32 v55, 1, v31
	s_nop 0
	v_cndmask_b32_e64 v19, v31, v19, s[0:1]
	v_fma_f32 v31, -v55, v31, v17
	v_cmp_lt_f32_e64 s[0:1], 0, v31
	s_nop 1
	v_cndmask_b32_e64 v19, v19, v55, s[0:1]
	v_mul_f32_e32 v31, 0x37800000, v19
	v_cndmask_b32_e32 v19, v19, v31, vcc
	v_cmp_class_f32_e32 vcc, v17, v54
	s_nop 1
	v_cndmask_b32_e32 v19, v19, v17, vcc
	v_div_scale_f32 v31, s[0:1], v19, v19, 1.0
	v_rcp_f32_e32 v55, v31
	ds_bpermute_b32 v17, v48, v16
	v_fma_f32 v18, -v31, v55, 1.0
	v_fmac_f32_e32 v55, v18, v55
	v_div_scale_f32 v18, vcc, 1.0, v19, 1.0
	v_mul_f32_e32 v56, v18, v55
	v_fma_f32 v58, -v31, v56, v18
	v_fmac_f32_e32 v56, v58, v55
	v_fma_f32 v18, -v31, v56, v18
	v_div_fmas_f32 v18, v18, v55, v56
	v_div_fixup_f32 v18, v18, v19, 1.0
	v_pk_mul_f32 v[60:61], v[18:19], v[60:61] op_sel_hi:[0,1]
	v_pk_mul_f32 v[62:63], v[18:19], v[62:63] op_sel_hi:[0,1]
	v_cvt_pk_bf16_f32 v60, v60, v61
	v_cvt_pk_bf16_f32 v61, v62, v63
	global_store_dwordx2 v[28:29], v[60:61], off offset:512 sc1
	v_pk_mul_f32 v[60:61], v[18:19], v[64:65] op_sel_hi:[0,1]
	v_pk_mul_f32 v[62:63], v[18:19], v[66:67] op_sel_hi:[0,1]
	v_cvt_pk_bf16_f32 v60, v60, v61
	v_cvt_pk_bf16_f32 v61, v62, v63
	v_mov_b32_e32 v56, v59
	v_pk_mul_f32 v[68:69], v[18:19], v[68:69] op_sel_hi:[0,1]
	v_pk_mul_f32 v[70:71], v[18:19], v[80:81] op_sel_hi:[0,1]
	global_store_dwordx2 v[28:29], v[60:61], off offset:1024 sc1
	v_pk_mul_f32 v[60:61], v[18:19], v[74:75] op_sel_hi:[0,1]
	v_pk_mul_f32 v[18:19], v[18:19], v[56:57] op_sel_hi:[0,1]
	v_cvt_pk_bf16_f32 v68, v68, v69
	v_cvt_pk_bf16_f32 v69, v70, v71
	v_cvt_pk_bf16_f32 v58, v60, v61
	v_cvt_pk_bf16_f32 v59, v18, v19
	global_store_dwordx2 v[28:29], v[68:69], off sc1
	global_store_dwordx2 v[28:29], v[58:59], off offset:1536 sc1
	s_cbranch_scc1 .LBB0_806
	s_waitcnt lgkmcnt(0)
	v_add_f32_e32 v16, v16, v17
	v_fmamk_f32 v16, v16, 0x3a800000, v53
	v_mul_f32_e32 v17, 0x4f800000, v16
	v_cmp_gt_f32_e32 vcc, s19, v16
	s_waitcnt vmcnt(8)
	v_lshlrev_b32_e32 v19, 16, v47
	s_waitcnt vmcnt(6)
	v_lshlrev_b32_e32 v57, 16, v44
	v_cndmask_b32_e32 v16, v16, v17, vcc
	v_sqrt_f32_e32 v18, v16
	v_and_b32_e32 v17, 0xffff0000, v47
	v_lshlrev_b32_e32 v47, 16, v46
	v_and_b32_e32 v59, 0xffff0000, v44
	v_add_u32_e32 v28, -1, v18
	v_fma_f32 v29, -v28, v18, v16
	v_cmp_ge_f32_e64 s[0:1], 0, v29
	v_add_u32_e32 v29, 1, v18
	v_lshlrev_b32_e32 v61, 16, v45
	v_cndmask_b32_e64 v28, v18, v28, s[0:1]
	v_fma_f32 v18, -v29, v18, v16
	v_cmp_lt_f32_e64 s[0:1], 0, v18
	v_and_b32_e32 v45, 0xffff0000, v45
	v_and_b32_e32 v44, 0xffff0000, v43
	v_cndmask_b32_e64 v18, v28, v29, s[0:1]
	v_mul_f32_e32 v28, 0x37800000, v18
	v_cndmask_b32_e32 v18, v18, v28, vcc
	v_cmp_class_f32_e32 vcc, v16, v54
	v_and_b32_e32 v29, 0xffff0000, v46
	v_lshlrev_b32_e32 v56, 16, v42
	v_cndmask_b32_e32 v16, v18, v16, vcc
	v_div_scale_f32 v18, s[0:1], v16, v16, 1.0
	v_rcp_f32_e32 v28, v18
	v_and_b32_e32 v58, 0xffff0000, v42
	v_lshlrev_b32_e32 v60, 16, v43
	s_waitcnt vmcnt(5)
	v_and_b32_e32 v63, 0xffff0000, v40
	v_fma_f32 v31, -v18, v28, 1.0
	v_fmac_f32_e32 v28, v31, v28
	v_div_scale_f32 v31, vcc, 1.0, v16, 1.0
	v_mul_f32_e32 v46, v31, v28
	v_fma_f32 v55, -v18, v46, v31
	v_fmac_f32_e32 v46, v55, v28
	v_fma_f32 v18, -v18, v46, v31
	v_div_fmas_f32 v18, v18, v28, v46
	v_div_fixup_f32 v31, v18, v16, 1.0
	v_pk_mul_f32 v[42:43], v[30:31], v[44:45]
	v_lshlrev_b32_e32 v45, 16, v40
	v_lshlrev_b32_e32 v65, 16, v41
	v_and_b32_e32 v41, 0xffff0000, v41
	v_and_b32_e32 v40, 0xffff0000, v39
	s_waitcnt vmcnt(4)
	v_lshlrev_b32_e32 v16, 16, v36
	v_lshlrev_b32_e32 v44, 16, v38
	v_and_b32_e32 v62, 0xffff0000, v38
	v_lshlrev_b32_e32 v64, 16, v39
	v_pk_mul_f32 v[38:39], v[30:31], v[40:41]
	v_mul_f32_e32 v41, v31, v16
	v_and_b32_e32 v16, 0xffff0000, v36
	v_mul_f32_e32 v67, v31, v16
	v_lshlrev_b32_e32 v16, 16, v37
	v_mul_f32_e32 v16, v31, v16
	v_mul_f32_e32 v69, v2, v16
	v_and_b32_e32 v16, 0xffff0000, v37
	v_mul_f32_e32 v16, v31, v16
	v_mul_f32_e32 v17, v30, v17
	v_mul_f32_e32 v37, v3, v16
	v_lshlrev_b32_e32 v72, 16, v35
	v_and_b32_e32 v73, 0xffff0000, v35
	v_mov_b32_e32 v16, v31
	v_pk_mul_f32 v[72:73], v[16:17], v[72:73] op_sel_hi:[0,1]
	v_lshlrev_b32_e32 v70, 16, v33
	v_and_b32_e32 v71, 0xffff0000, v33
	v_pk_mul_f32 v[72:73], v[14:15], v[72:73]
	v_and_b32_e32 v33, 0xffff0000, v34
	v_pk_fma_f32 v[70:71], v[30:31], v[70:71], v[72:73] op_sel_hi:[0,1,1]
	v_lshlrev_b32_e32 v72, 16, v32
	v_and_b32_e32 v73, 0xffff0000, v32
	v_lshlrev_b32_e32 v32, 16, v34
	v_pk_mul_f32 v[32:33], v[16:17], v[32:33] op_sel_hi:[0,1]
	v_pk_mul_f32 v[32:33], v[12:13], v[32:33]
	v_mov_b32_e32 v40, v71
	v_pk_fma_f32 v[32:33], v[30:31], v[72:73], v[32:33] op_sel_hi:[0,1,1]
	v_pk_mov_b32 v[72:73], v[70:71], v[0:1] op_sel:[1,0]
	v_pk_mov_b32 v[78:79], v[32:33], v[0:1] op_sel:[1,0]
	v_pk_mul_f32 v[72:73], v[72:73], v[40:41]
	v_mov_b32_e32 v40, v33
	v_mov_b32_e32 v34, v70
	v_mov_b32_e32 v35, v30
	v_mov_b32_e32 v46, v70
	v_mov_b32_e32 v74, v32
	v_mov_b32_e32 v75, v30
	v_mov_b32_e32 v76, v32
	v_mov_b32_e32 v77, v47
	v_pk_mul_f32 v[40:41], v[78:79], v[40:41]
	v_pk_fma_f32 v[34:35], v[34:35], v[46:47], v[72:73]
	v_pk_fma_f32 v[40:41], v[74:75], v[76:77], v[40:41]
	v_pk_mul_f32 v[60:61], v[30:31], v[60:61]
	v_pk_add_f32 v[46:47], v[40:41], v[34:35]
	v_pk_mul_f32 v[34:35], v[40:41], v[34:35]
	v_pk_mul_f32 v[56:57], v[30:31], v[56:57]
	v_pk_mul_f32 v[58:59], v[30:31], v[58:59]
	v_mov_b32_e32 v47, v35
	v_mov_b32_e32 v34, v61
	v_mov_b32_e32 v35, v43
	v_mov_b32_e32 v61, v42
	v_pk_fma_f32 v[34:35], v[10:11], v[34:35], v[60:61]
	v_mov_b32_e32 v60, v57
	v_mov_b32_e32 v61, v59
	v_mov_b32_e32 v57, v58
	v_pk_fma_f32 v[56:57], v[8:9], v[60:61], v[56:57]
	v_mov_b32_e32 v61, v1
	v_mov_b32_e32 v60, v57
	v_mov_b32_e32 v66, v57
	v_mov_b32_e32 v42, v35
	v_mov_b32_e32 v43, v1
	v_mov_b32_e32 v58, v56
	v_mov_b32_e32 v59, v30
	v_mov_b32_e32 v28, v56
	v_pk_mul_f32 v[60:61], v[60:61], v[66:67]
	v_mov_b32_e32 v66, v35
	v_mul_f32_e32 v19, v30, v19
	v_pk_mul_f32 v[44:45], v[30:31], v[44:45]
	v_pk_mul_f32 v[62:63], v[30:31], v[62:63]
	v_pk_mul_f32 v[64:65], v[30:31], v[64:65]
	v_pk_fma_f32 v[58:59], v[58:59], v[28:29], v[60:61]
	v_mov_b32_e32 v60, v34
	v_mov_b32_e32 v61, v30
	v_mov_b32_e32 v28, v34
	v_pk_mul_f32 v[30:31], v[42:43], v[66:67]
	s_ashr_i32 s13, s12, 31
	v_pk_fma_f32 v[28:29], v[60:61], v[28:29], v[30:31]
	s_nop 0
	v_pk_add_f32 v[30:31], v[58:59], v[28:29]
	v_pk_mul_f32 v[28:29], v[58:59], v[28:29]
	v_mov_b32_e32 v58, v41
	v_mov_b32_e32 v31, v29
	v_pk_add_f32 v[28:29], v[46:47], v[30:31]
	v_mov_b32_e32 v30, v65
	v_mov_b32_e32 v31, v39
	v_mov_b32_e32 v65, v38
	v_pk_fma_f32 v[30:31], v[6:7], v[30:31], v[64:65]
	s_nop 0
	v_mov_b32_e32 v36, v30
	v_mov_b32_e32 v16, v30
	v_pk_add_f32 v[16:17], v[36:37], v[16:17]
	v_mul_f32_e32 v18, v31, v31
	v_pk_fma_f32 v[36:37], v[30:31], v[30:31], v[18:19] op_sel_hi:[1,1,0]
	v_pk_mul_f32 v[38:39], v[16:17], v[16:17]
	s_nop 0
	v_mov_b32_e32 v37, v39
	v_mov_b32_e32 v38, v45
	v_mov_b32_e32 v39, v63
	v_mov_b32_e32 v45, v62
	v_pk_fma_f32 v[38:39], v[4:5], v[38:39], v[44:45]
	s_nop 0
	v_mov_b32_e32 v68, v38
	v_mov_b32_e32 v18, v38
	v_pk_add_f32 v[18:19], v[68:69], v[18:19]
	v_mul_f32_e32 v16, v39, v39
	v_pk_fma_f32 v[42:43], v[38:39], v[38:39], v[16:17] op_sel_hi:[1,1,0]
	v_pk_mul_f32 v[44:45], v[18:19], v[18:19]
	s_nop 0
	v_mov_b32_e32 v43, v45
	v_pk_add_f32 v[36:37], v[42:43], v[36:37]
	s_nop 0
	v_pk_add_f32 v[28:29], v[28:29], v[36:37]
	s_nop 0
	v_add_f32_e32 v16, v28, v29
	ds_bpermute_b32 v18, v20, v16
	s_waitcnt lgkmcnt(0)
	v_add_f32_e32 v16, v16, v18
	ds_bpermute_b32 v18, v48, v16
	s_waitcnt lgkmcnt(0)
	v_add_f32_e32 v16, v16, v18
	ds_bpermute_b32 v18, v49, v16
	s_waitcnt lgkmcnt(0)
	v_add_f32_e32 v16, v16, v18
	ds_bpermute_b32 v18, v50, v16
	s_waitcnt lgkmcnt(0)
	v_add_f32_e32 v16, v16, v18
	ds_bpermute_b32 v18, v51, v16
	s_waitcnt lgkmcnt(0)
	v_add_f32_e32 v16, v16, v18
	ds_bpermute_b32 v18, v52, v16
	s_waitcnt lgkmcnt(0)
	v_add_f32_e32 v16, v16, v18
	v_fmamk_f32 v16, v16, 0x3a800000, v53
	v_mul_f32_e32 v18, 0x4f800000, v16
	v_cmp_gt_f32_e32 vcc, s19, v16
	s_nop 1
	v_cndmask_b32_e32 v16, v16, v18, vcc
	v_sqrt_f32_e32 v18, v16
	s_nop 0
	v_add_u32_e32 v28, -1, v18
	v_fma_f32 v29, -v28, v18, v16
	v_cmp_ge_f32_e64 s[0:1], 0, v29
	v_add_u32_e32 v29, 1, v18
	s_nop 0
	v_cndmask_b32_e64 v28, v18, v28, s[0:1]
	v_fma_f32 v18, -v29, v18, v16
	v_cmp_lt_f32_e64 s[0:1], 0, v18
	s_nop 1
	v_cndmask_b32_e64 v18, v28, v29, s[0:1]
	v_mul_f32_e32 v28, 0x37800000, v18
	v_cndmask_b32_e32 v18, v18, v28, vcc
	v_cmp_class_f32_e32 vcc, v16, v54
	s_nop 1
	v_cndmask_b32_e32 v16, v18, v16, vcc
	v_div_scale_f32 v18, s[0:1], v16, v16, 1.0
	v_rcp_f32_e32 v36, v18
	s_lshl_b64 s[0:1], s[12:13], 11
	v_lshl_add_u64 v[28:29], v[22:23], 0, s[0:1]
	v_fma_f32 v37, -v18, v36, 1.0
	v_fmac_f32_e32 v36, v37, v36
	v_div_scale_f32 v37, vcc, 1.0, v16, 1.0
	v_mul_f32_e32 v40, v37, v36
	v_fma_f32 v42, -v18, v40, v37
	v_fmac_f32_e32 v40, v42, v36
	v_fma_f32 v18, -v18, v40, v37
	v_div_fmas_f32 v18, v18, v36, v40
	v_div_fixup_f32 v18, v18, v16, 1.0
	v_pk_mul_f32 v[32:33], v[18:19], v[32:33] op_sel_hi:[0,1]
	v_pk_mul_f32 v[36:37], v[18:19], v[70:71] op_sel_hi:[0,1]
	v_cvt_pk_bf16_f32 v32, v32, v33
	v_cvt_pk_bf16_f32 v33, v36, v37
	global_store_dwordx2 v[28:29], v[32:33], off sc1
	v_pk_mul_f32 v[32:33], v[18:19], v[56:57] op_sel_hi:[0,1]
	v_pk_mul_f32 v[34:35], v[18:19], v[34:35] op_sel_hi:[0,1]
	v_cvt_pk_bf16_f32 v32, v32, v33
	v_cvt_pk_bf16_f32 v33, v34, v35
	global_store_dwordx2 v[28:29], v[32:33], off offset:512 sc1
	v_pk_mul_f32 v[32:33], v[18:19], v[38:39] op_sel_hi:[0,1]
	v_pk_mul_f32 v[30:31], v[18:19], v[30:31] op_sel_hi:[0,1]
	v_mov_b32_e32 v16, v19
	v_cvt_pk_bf16_f32 v32, v32, v33
	v_cvt_pk_bf16_f32 v33, v30, v31
	v_pk_mul_f32 v[30:31], v[18:19], v[58:59] op_sel_hi:[0,1]
	v_pk_mul_f32 v[16:17], v[18:19], v[16:17] op_sel_hi:[0,1]
	v_cvt_pk_bf16_f32 v30, v30, v31
	v_cvt_pk_bf16_f32 v31, v16, v17
	global_store_dwordx2 v[28:29], v[32:33], off offset:1024 sc1
	global_store_dwordx2 v[28:29], v[30:31], off offset:1536 sc1
	s_branch .LBB0_806
